# speedup vs baseline: 1.0078x; 1.0023x over previous
; __device__ __forceinline__ unsigned short f2bf(float f) { return (unsigned short)(cvt_pk_bf16(f, 0.f) & 0xffffu); }
; __device__ __forceinline__ float log2_gamma(int h) { return log2f(1.0f - exp2f(-5.0f - (float)h)); }
; template <bool SCALE> __device__ __forceinline__ void tile_load_t(bf16_t* dst, const bf16_t* src, size_t ld, float l2g, int tid) {
; #pragma unroll
;     for (int i = 0; i < 4; ++i) { const int ch = tid + 512 * i, r = ch >> 4, c0 = (ch & 15) * 8;
;         const u32x4 raw = *(const u32x4*)(src + (size_t)r * ld + c0);
;         float f[8]; unpack8(raw, f);
;         if (SCALE) { const float z = exp2f(l2g * (float)(127 - r));
; #pragma unroll
;             for (int j = 0; j < 8; ++j) f[j] *= z; }
; #pragma unroll
;         for (int j = 0; j < 8; ++j) dst[(c0 + j) * TS + r] = f2bf(f[j]); }
; }
; __device__ __forceinline__ void ret_stepA(const Params& p, unsigned char* smem, int u) {
;     ...
;     const int bh = u >> 6, n = u & 63, b = bh >> 3, h = bh & 7;
;     const bf16_t* proj = (const bf16_t*)(p.ws + WS_PROJ) + (size_t)(b * SEQ + n * 128) * INP;
;     bf16_t* kT = (bf16_t*)smem; bf16_t* vT = (bf16_t*)(smem + TILE_B);
;     const float l2g = log2_gamma(h);
;     tile_load_t<true>(kT, proj + C_RK + h * 128, INP, l2g, tid);
.LBB0_220:
	s_bfe_u32 s8, s39, 0x30006
	v_cvt_f32_ubyte0_e32 v0, s8
	v_sub_f32_e32 v0, 0xc0a00000, v0
	v_mov_b32_e32 v7, v166
	v_cmp_gt_f32_e32 vcc, s26, v0
	s_and_b32 s4, s36, 0xffffe000
	s_and_b32 s5, s35, 0x1f80
	v_cndmask_b32_e32 v13, 0, v4, vcc
	v_lshlrev_b32_e32 v2, 3, v7
	v_add_u32_e32 v3, 0x200, v7
	v_add_u32_e32 v8, 0x400, v7
	v_add_u32_e32 v9, 0x600, v7
	v_and_b32_e32 v10, 15, v7
	v_lshrrev_b32_e32 v11, 1, v7
	v_ashrrev_i32_e32 v12, 2, v7
	v_and_b32_e32 v76, 48, v7
	s_or_b32 s10, s4, s5
	v_and_b32_e32 v2, 0x78, v2
	v_ashrrev_i32_e32 v22, 4, v3
	v_ashrrev_i32_e32 v24, 4, v8
	v_ashrrev_i32_e32 v26, 4, v9
	v_and_or_b32 v3, v11, s30, v10
	v_add_u32_e32 v8, 0, v76
	v_and_or_b32 v77, v12, s27, v10
	v_add_f32_e32 v9, v0, v13
	s_mul_hi_i32 s9, s10, 0x3600
	s_mulk_i32 s10, 0x3600
	v_lshlrev_b32_e32 v0, 1, v2
	v_mul_u32_u24_e32 v10, 0x110, v2
	v_mad_u32_u24 v18, v2, s29, 0
	v_mul_u32_u24_e32 v19, 0x88, v3
	v_mad_u64_u32 v[2:3], s[4:5], v77, s29, v[8:9]
	s_add_u32 s10, s37, s10
	v_exp_f32_e32 v3, v9
	s_addc_u32 s9, s38, s9
	s_and_b64 s[4:5], vcc, exec
	s_cselect_b32 s4, 0xffffffc0, 0
	v_ldexp_f32 v3, v3, s4
	v_sub_f32_e32 v3, 1.0, v3
	v_cmp_gt_f32_e32 vcc, s28, v3
	s_and_b64 s[4:5], vcc, exec
	s_cselect_b32 s4, 32, 0
	s_lshl_b32 s5, s8, 8
	v_ashrrev_i32_e32 v20, 4, v7
	v_ldexp_f32 v3, v3, s4
	s_add_u32 s4, s10, s5
	v_sub_u32_e32 v14, 0x7f, v20
	s_addc_u32 s5, s9, 0
	v_lshlrev_b32_e32 v15, 1, v20
	v_cvt_f32_i32_e32 v27, v14
	v_sub_u32_e32 v11, 0x7f, v22
	v_lshlrev_b32_e32 v12, 1, v22
	v_lshlrev_b32_e32 v14, 1, v24
	v_lshlrev_b32_e32 v17, 1, v26
	v_lshl_add_u32 v68, v19, 1, v8
	v_lshl_add_u64 v[8:9], s[4:5], 0, v[0:1]
	v_sub_u32_e32 v13, 0x7f, v24
	v_sub_u32_e32 v16, 0x7f, v26
	v_add3_u32 v28, 0, v15, v10
	v_cvt_f32_i32_e32 v29, v11
	v_add3_u32 v30, 0, v12, v10
	v_add3_u32 v32, 0, v14, v10
	v_add3_u32 v34, 0, v17, v10
	v_mad_i64_i32 v[10:11], s[4:5], v20, s25, v[8:9]
	v_cvt_f32_i32_e32 v31, v13
	v_cvt_f32_i32_e32 v33, v16
	v_add_u32_e32 v35, v18, v15
	v_add_u32_e32 v36, v18, v12
	v_add_u32_e32 v37, v18, v14
	v_add_u32_e32 v38, v18, v17
	v_mad_i64_i32 v[12:13], s[4:5], v22, s25, v[8:9]
	v_mad_i64_i32 v[14:15], s[4:5], v24, s25, v[8:9]
	v_mad_i64_i32 v[16:17], s[4:5], v26, s25, v[8:9]
	v_lshl_add_u64 v[18:19], v[8:9], 0, s[16:17]
	v_log_f32_e32 v3, v3
	v_cndmask_b32_e32 v39, 0, v5, vcc
	v_mad_i64_i32 v[20:21], s[4:5], v20, s25, v[18:19]
	v_sub_f32_e32 v0, v3, v39
	v_mad_i64_i32 v[22:23], s[4:5], v22, s25, v[18:19]
	v_mad_i64_i32 v[24:25], s[4:5], v24, s25, v[18:19]
	v_mad_i64_i32 v[18:19], s[4:5], v26, s25, v[18:19]
	global_load_dwordx4 v[80:83], v[10:11], off offset:2048
	global_load_dwordx4 v[84:87], v[12:13], off offset:2048
	global_load_dwordx4 v[88:91], v[14:15], off offset:2048
	global_load_dwordx4 v[92:95], v[16:17], off offset:2048
	global_load_dwordx4 v[96:99], v[20:21], off
	global_load_dwordx4 v[100:103], v[22:23], off
	global_load_dwordx4 v[104:107], v[24:25], off
	global_load_dwordx4 v[108:111], v[18:19], off
	v_mul_f32_e32 v3, v0, v27
	v_mul_f32_e32 v26, v0, v29
	v_mul_f32_e32 v39, v0, v31
	v_mul_f32_e32 v40, v0, v33
	v_cmp_gt_f32_e32 vcc, s26, v3
	v_cmp_gt_f32_e64 s[8:9], s26, v26
	v_cmp_gt_f32_e64 s[10:11], s26, v39
	v_cndmask_b32_e32 v3, 0, v4, vcc
	v_cndmask_b32_e64 v26, 0, v4, s[8:9]
	v_cmp_gt_f32_e64 s[12:13], s26, v40
	v_cndmask_b32_e64 v39, 0, v4, s[10:11]
	v_fmac_f32_e32 v3, v0, v27
	v_cndmask_b32_e64 v40, 0, v4, s[12:13]
	v_fmac_f32_e32 v26, v0, v29
	v_fmac_f32_e32 v39, v0, v31
	v_fmac_f32_e32 v40, v0, v33
	v_exp_f32_e32 v3, v3
	v_exp_f32_e32 v26, v26
	v_exp_f32_e32 v33, v39
	v_exp_f32_e32 v39, v40
	v_cndmask_b32_e32 v27, 0, v6, vcc
	v_cndmask_b32_e64 v29, 0, v6, s[8:9]
	v_cndmask_b32_e64 v31, 0, v6, s[10:11]
	v_cndmask_b32_e64 v0, 0, v6, s[12:13]
	v_ldexp_f32 v3, v3, v27
	v_ldexp_f32 v26, v26, v29
	v_ldexp_f32 v27, v33, v31
	v_ldexp_f32 v0, v39, v0
	s_add_i32 s39, s39, s44
	s_add_i32 s36, s36, s68
	s_add_i32 s35, s35, s73
	s_waitcnt vmcnt(7)
	v_mov_b64_e32 v[8:9], v[80:81]
	v_mov_b64_e32 v[10:11], v[82:83]
	v_lshlrev_b32_e32 v29, 16, v8
	v_and_b32_e32 v8, 0xffff0000, v8
	v_lshlrev_b32_e32 v31, 16, v9
	v_and_b32_e32 v9, 0xffff0000, v9
	v_lshlrev_b32_e32 v33, 16, v10
	v_and_b32_e32 v10, 0xffff0000, v10
	v_lshlrev_b32_e32 v39, 16, v11
	v_and_b32_e32 v11, 0xffff0000, v11
	v_mul_f32_e32 v8, v3, v8
	v_mul_f32_e32 v29, v3, v29
	v_mul_f32_e32 v31, v3, v31
	v_mul_f32_e32 v9, v3, v9
	v_mul_f32_e32 v33, v3, v33
	v_mul_f32_e32 v10, v3, v10
	v_mul_f32_e32 v39, v3, v39
	v_mul_f32_e32 v3, v3, v11
	v_cvt_pk_bf16_f32 v11, v29, v1
	ds_write_b16 v28, v11
	v_cvt_pk_bf16_f32 v8, v8, v1
	ds_write_b16 v28, v8 offset:272
	v_cvt_pk_bf16_f32 v8, v31, v1
	ds_write_b16 v28, v8 offset:544
	v_cvt_pk_bf16_f32 v8, v9, v1
	ds_write_b16 v28, v8 offset:816
	v_cvt_pk_bf16_f32 v8, v33, v1
	ds_write_b16 v28, v8 offset:1088
	v_cvt_pk_bf16_f32 v8, v10, v1
	ds_write_b16 v28, v8 offset:1360
	v_cvt_pk_bf16_f32 v8, v39, v1
	ds_write_b16 v28, v8 offset:1632
	v_cvt_pk_bf16_f32 v3, v3, v1
	ds_write_b16 v28, v3 offset:1904
	s_waitcnt vmcnt(6)
	v_mov_b64_e32 v[8:9], v[84:85]
	v_mov_b64_e32 v[10:11], v[86:87]
	v_lshlrev_b32_e32 v3, 16, v8
	v_mul_f32_e32 v3, v26, v3
	v_and_b32_e32 v8, 0xffff0000, v8
	v_cvt_pk_bf16_f32 v3, v3, v1
	v_lshlrev_b32_e32 v12, 16, v9
	v_mul_f32_e32 v8, v26, v8
	ds_write_b16 v30, v3
	v_cvt_pk_bf16_f32 v3, v8, v1
	v_and_b32_e32 v9, 0xffff0000, v9
	v_mul_f32_e32 v12, v26, v12
	ds_write_b16 v30, v3 offset:272
	v_cvt_pk_bf16_f32 v3, v12, v1
	v_lshlrev_b32_e32 v13, 16, v10
	v_mul_f32_e32 v9, v26, v9
	ds_write_b16 v30, v3 offset:544
	v_cvt_pk_bf16_f32 v3, v9, v1
	v_and_b32_e32 v10, 0xffff0000, v10
	v_mul_f32_e32 v13, v26, v13
	ds_write_b16 v30, v3 offset:816
	v_cvt_pk_bf16_f32 v3, v13, v1
	v_lshlrev_b32_e32 v28, 16, v11
	v_and_b32_e32 v11, 0xffff0000, v11
	v_mul_f32_e32 v10, v26, v10
	ds_write_b16 v30, v3 offset:1088
	v_cvt_pk_bf16_f32 v3, v10, v1
	v_mul_f32_e32 v28, v26, v28
	v_mul_f32_e32 v11, v26, v11
	ds_write_b16 v30, v3 offset:1360
	v_cvt_pk_bf16_f32 v3, v28, v1
	ds_write_b16 v30, v3 offset:1632
	v_cvt_pk_bf16_f32 v3, v11, v1
	ds_write_b16 v30, v3 offset:1904
	s_waitcnt vmcnt(5)
; __device__ __forceinline__ unsigned short f2bf(float f) { return (unsigned short)(cvt_pk_bf16(f, 0.f) & 0xffffu); }
; template <bool SCALE> __device__ __forceinline__ void tile_load_t(bf16_t* dst, const bf16_t* src, size_t ld, float l2g, int tid) {
; #pragma unroll
;     for (int i = 0; i < 4; ++i) { const int ch = tid + 512 * i, r = ch >> 4, c0 = (ch & 15) * 8;
;         const u32x4 raw = *(const u32x4*)(src + (size_t)r * ld + c0);
;         float f[8]; unpack8(raw, f);
;         if (SCALE) { const float z = exp2f(l2g * (float)(127 - r));
; #pragma unroll
;             for (int j = 0; j < 8; ++j) f[j] *= z; }
; #pragma unroll
;         for (int j = 0; j < 8; ++j) dst[(c0 + j) * TS + r] = f2bf(f[j]); }
; }
; __device__ __forceinline__ void ret_stepA(const Params& p, unsigned char* smem, int u) {
;     ...
;     tile_load_t<true>(kT, proj + C_RK + h * 128, INP, l2g, tid);
;     tile_load_t<false>(vT, proj + C_RV + h * 128, INP, 0.f, tid);
;     __syncthreads();
	v_mov_b64_e32 v[8:9], v[88:89]
	v_mov_b64_e32 v[10:11], v[90:91]
	v_lshlrev_b32_e32 v3, 16, v8
	v_mul_f32_e32 v3, v27, v3
	v_and_b32_e32 v8, 0xffff0000, v8
	v_cvt_pk_bf16_f32 v3, v3, v1
	v_lshlrev_b32_e32 v12, 16, v9
	v_mul_f32_e32 v8, v27, v8
	ds_write_b16 v32, v3
	v_cvt_pk_bf16_f32 v3, v8, v1
	v_and_b32_e32 v9, 0xffff0000, v9
	v_mul_f32_e32 v12, v27, v12
	ds_write_b16 v32, v3 offset:272
	v_cvt_pk_bf16_f32 v3, v12, v1
	v_lshlrev_b32_e32 v13, 16, v10
	v_mul_f32_e32 v9, v27, v9
	ds_write_b16 v32, v3 offset:544
	v_cvt_pk_bf16_f32 v3, v9, v1
	v_and_b32_e32 v10, 0xffff0000, v10
	v_mul_f32_e32 v13, v27, v13
	ds_write_b16 v32, v3 offset:816
	v_cvt_pk_bf16_f32 v3, v13, v1
	v_lshlrev_b32_e32 v14, 16, v11
	v_and_b32_e32 v11, 0xffff0000, v11
	v_mul_f32_e32 v10, v27, v10
	ds_write_b16 v32, v3 offset:1088
	v_cvt_pk_bf16_f32 v3, v10, v1
	v_mul_f32_e32 v14, v27, v14
	v_mul_f32_e32 v11, v27, v11
	ds_write_b16 v32, v3 offset:1360
	v_cvt_pk_bf16_f32 v3, v14, v1
	ds_write_b16 v32, v3 offset:1632
	v_cvt_pk_bf16_f32 v3, v11, v1
	ds_write_b16 v32, v3 offset:1904
	s_waitcnt vmcnt(4)
	v_mov_b64_e32 v[8:9], v[92:93]
	v_mov_b64_e32 v[10:11], v[94:95]
	v_lshlrev_b32_e32 v3, 16, v8
	v_mul_f32_e32 v3, v0, v3
	v_and_b32_e32 v8, 0xffff0000, v8
	v_cvt_pk_bf16_f32 v3, v3, v1
	v_lshlrev_b32_e32 v12, 16, v9
	v_mul_f32_e32 v8, v0, v8
	ds_write_b16 v34, v3
	v_cvt_pk_bf16_f32 v3, v8, v1
	v_and_b32_e32 v9, 0xffff0000, v9
	v_mul_f32_e32 v12, v0, v12
	ds_write_b16 v34, v3 offset:272
	v_cvt_pk_bf16_f32 v3, v12, v1
	v_lshlrev_b32_e32 v13, 16, v10
	v_mul_f32_e32 v9, v0, v9
	ds_write_b16 v34, v3 offset:544
	v_cvt_pk_bf16_f32 v3, v9, v1
	v_and_b32_e32 v10, 0xffff0000, v10
	v_lshlrev_b32_e32 v14, 16, v11
	v_and_b32_e32 v11, 0xffff0000, v11
	v_mul_f32_e32 v13, v0, v13
	ds_write_b16 v34, v3 offset:816
	v_cvt_pk_bf16_f32 v3, v13, v1
	v_mul_f32_e32 v10, v0, v10
	v_mul_f32_e32 v14, v0, v14
	v_mul_f32_e32 v0, v0, v11
	ds_write_b16 v34, v3 offset:1088
	v_cvt_pk_bf16_f32 v3, v10, v1
	ds_write_b16 v34, v3 offset:1360
	v_cvt_pk_bf16_f32 v3, v14, v1
	ds_write_b16 v34, v3 offset:1632
	v_cvt_pk_bf16_f32 v0, v0, v1
	ds_write_b16 v34, v0 offset:1904
	s_waitcnt vmcnt(3)
	v_mov_b64_e32 v[8:9], v[96:97]
	v_mov_b64_e32 v[10:11], v[98:99]
	v_lshlrev_b32_e32 v0, 16, v8
	v_cvt_pk_bf16_f32 v0, v0, v1
	v_and_b32_e32 v3, 0xffff0000, v8
	ds_write_b16 v35, v0 offset:34816
	v_cvt_pk_bf16_f32 v0, v3, v1
	v_lshlrev_b32_e32 v8, 16, v9
	ds_write_b16 v35, v0 offset:35088
	v_cvt_pk_bf16_f32 v0, v8, v1
	v_and_b32_e32 v9, 0xffff0000, v9
	ds_write_b16 v35, v0 offset:35360
	v_cvt_pk_bf16_f32 v0, v9, v1
	v_lshlrev_b32_e32 v12, 16, v10
	ds_write_b16 v35, v0 offset:35632
	v_cvt_pk_bf16_f32 v0, v12, v1
	v_and_b32_e32 v10, 0xffff0000, v10
	ds_write_b16 v35, v0 offset:35904
	v_cvt_pk_bf16_f32 v0, v10, v1
	v_lshlrev_b32_e32 v13, 16, v11
	v_and_b32_e32 v11, 0xffff0000, v11
	ds_write_b16 v35, v0 offset:36176
	v_cvt_pk_bf16_f32 v0, v13, v1
	ds_write_b16 v35, v0 offset:36448
	v_cvt_pk_bf16_f32 v0, v11, v1
	ds_write_b16 v35, v0 offset:36720
	s_waitcnt vmcnt(2)
	v_mov_b64_e32 v[8:9], v[100:101]
	v_mov_b64_e32 v[10:11], v[102:103]
	v_lshlrev_b32_e32 v0, 16, v8
	v_cvt_pk_bf16_f32 v0, v0, v1
	v_and_b32_e32 v3, 0xffff0000, v8
	ds_write_b16 v36, v0 offset:34816
	v_cvt_pk_bf16_f32 v0, v3, v1
	v_lshlrev_b32_e32 v8, 16, v9
	ds_write_b16 v36, v0 offset:35088
	v_cvt_pk_bf16_f32 v0, v8, v1
	v_and_b32_e32 v9, 0xffff0000, v9
	ds_write_b16 v36, v0 offset:35360
	v_cvt_pk_bf16_f32 v0, v9, v1
	v_lshlrev_b32_e32 v12, 16, v10
	ds_write_b16 v36, v0 offset:35632
	v_cvt_pk_bf16_f32 v0, v12, v1
	v_and_b32_e32 v10, 0xffff0000, v10
	ds_write_b16 v36, v0 offset:35904
	v_cvt_pk_bf16_f32 v0, v10, v1
	v_lshlrev_b32_e32 v13, 16, v11
	v_and_b32_e32 v11, 0xffff0000, v11
	ds_write_b16 v36, v0 offset:36176
	v_cvt_pk_bf16_f32 v0, v13, v1
	ds_write_b16 v36, v0 offset:36448
	v_cvt_pk_bf16_f32 v0, v11, v1
	ds_write_b16 v36, v0 offset:36720
	s_waitcnt vmcnt(1)
	v_mov_b64_e32 v[8:9], v[104:105]
	v_mov_b64_e32 v[10:11], v[106:107]
	v_lshlrev_b32_e32 v0, 16, v8
	v_cvt_pk_bf16_f32 v0, v0, v1
	v_and_b32_e32 v3, 0xffff0000, v8
	ds_write_b16 v37, v0 offset:34816
	v_cvt_pk_bf16_f32 v0, v3, v1
	v_lshlrev_b32_e32 v8, 16, v9
	ds_write_b16 v37, v0 offset:35088
	v_cvt_pk_bf16_f32 v0, v8, v1
	v_and_b32_e32 v9, 0xffff0000, v9
	ds_write_b16 v37, v0 offset:35360
	v_cvt_pk_bf16_f32 v0, v9, v1
	v_lshlrev_b32_e32 v12, 16, v10
	ds_write_b16 v37, v0 offset:35632
	v_cvt_pk_bf16_f32 v0, v12, v1
	v_and_b32_e32 v10, 0xffff0000, v10
	ds_write_b16 v37, v0 offset:35904
	v_cvt_pk_bf16_f32 v0, v10, v1
	v_lshlrev_b32_e32 v13, 16, v11
	v_and_b32_e32 v11, 0xffff0000, v11
	ds_write_b16 v37, v0 offset:36176
	v_cvt_pk_bf16_f32 v0, v13, v1
	ds_write_b16 v37, v0 offset:36448
	v_cvt_pk_bf16_f32 v0, v11, v1
	ds_write_b16 v37, v0 offset:36720
	s_waitcnt vmcnt(0)
	v_mov_b64_e32 v[8:9], v[108:109]
	v_mov_b64_e32 v[10:11], v[110:111]
	v_lshlrev_b32_e32 v0, 16, v8
	v_cvt_pk_bf16_f32 v0, v0, v1
	v_and_b32_e32 v3, 0xffff0000, v8
	ds_write_b16 v38, v0 offset:34816
	v_cvt_pk_bf16_f32 v0, v3, v1
	v_lshlrev_b32_e32 v8, 16, v9
	ds_write_b16 v38, v0 offset:35088
	v_cvt_pk_bf16_f32 v0, v8, v1
	v_and_b32_e32 v9, 0xffff0000, v9
	ds_write_b16 v38, v0 offset:35360
	v_cvt_pk_bf16_f32 v0, v9, v1
	v_lshlrev_b32_e32 v12, 16, v10
	ds_write_b16 v38, v0 offset:35632
	v_cvt_pk_bf16_f32 v0, v12, v1
	v_and_b32_e32 v10, 0xffff0000, v10
	ds_write_b16 v38, v0 offset:35904
	v_cvt_pk_bf16_f32 v0, v10, v1
	v_lshlrev_b32_e32 v13, 16, v11
	v_and_b32_e32 v11, 0xffff0000, v11
	ds_write_b16 v38, v0 offset:36176
	v_cvt_pk_bf16_f32 v0, v13, v1
	ds_write_b16 v38, v0 offset:36448
	v_cvt_pk_bf16_f32 v0, v11, v1
	ds_write_b16 v38, v0 offset:36720
	s_waitcnt lgkmcnt(0)
	s_barrier
; __device__ __forceinline__ void tile_mma(f32x4 (&acc)[4][2], const bf16_t* X, int xr0, const bf16_t* Y, int yr0, int fr, int fq) {
; #pragma unroll
;     for (int ks = 0; ks < 4; ++ks) {
;         u32x4 xf[2], yf[4];
; #pragma unroll
;         for (int n = 0; n < 2; ++n) xf[n] = *(const u32x4*)(X + (xr0 + n * 16 + fr) * TS + ks * 32 + fq * 8);
; #pragma unroll
;         for (int m = 0; m < 4; ++m) yf[m] = *(const u32x4*)(Y + (yr0 + m * 16 + fr) * TS + ks * 32 + fq * 8);
; #pragma unroll
;         for (int m = 0; m < 4; ++m)
; #pragma unroll
;             for (int n = 0; n < 2; ++n) acc[m][n] = mfma16(xf[n], yf[m], acc[m][n]);
;     }
; }
; __device__ __forceinline__ void ret_stepA(const Params& p, unsigned char* smem, int u) {
;     ...
;     f32x4 acc[4][2];
; #pragma unroll
;     for (int m = 0; m < 4; ++m) { acc[m][0] = (f32x4){0, 0, 0, 0}; acc[m][1] = (f32x4){0, 0, 0, 0}; }
;     tile_mma(acc, kT, wc * 32, vT, wr * 64, fr, fq);
;     float* S = (float*)(p.ws + WS_H) + (size_t)u * 16384;
; #pragma unroll
;     for (int m = 0; m < 4; ++m)
; #pragma unroll
;         for (int nn = 0; nn < 2; ++nn) *(f32x4*)(S + (wr * 64 + m * 16 + fr) * 128 + wc * 32 + nn * 16 + fq * 4) = acc[m][nn];
;     __syncthreads();
	ds_read_b128 v[8:11], v68
	ds_read_b128 v[12:15], v2 offset:34816
	ds_read_b128 v[16:19], v68 offset:64
	ds_read_b128 v[20:23], v2 offset:34880
	ds_read_b128 v[28:31], v68 offset:4352
	ds_read_b128 v[32:35], v68 offset:4416
	ds_read_b128 v[36:39], v2 offset:39168
	ds_read_b128 v[40:43], v2 offset:39232
	ds_read_b128 v[48:51], v2 offset:43520
	ds_read_b128 v[52:55], v2 offset:43584
	ds_read_b128 v[60:63], v2 offset:47872
	ds_read_b128 v[64:67], v2 offset:47936
	s_waitcnt lgkmcnt(10)
	v_mfma_f32_16x16x32_bf16 v[24:27], v[8:11], v[12:15], 0
	v_lshlrev_b32_e32 v0, 1, v7
	v_and_b32_e32 v0, 0x180, v0
	s_waitcnt lgkmcnt(7)
	v_mfma_f32_16x16x32_bf16 v[12:15], v[28:31], v[12:15], 0
	s_waitcnt lgkmcnt(5)
	v_mfma_f32_16x16x32_bf16 v[44:47], v[8:11], v[36:39], 0
	v_mfma_f32_16x16x32_bf16 v[36:39], v[28:31], v[36:39], 0
	s_waitcnt lgkmcnt(3)
	v_mfma_f32_16x16x32_bf16 v[56:59], v[8:11], v[48:51], 0
	s_waitcnt lgkmcnt(1)
	v_mfma_f32_16x16x32_bf16 v[8:11], v[8:11], v[60:63], 0
	v_mfma_f32_16x16x32_bf16 v[24:27], v[16:19], v[20:23], v[24:27]
	v_mfma_f32_16x16x32_bf16 v[12:15], v[32:35], v[20:23], v[12:15]
	v_mfma_f32_16x16x32_bf16 v[20:23], v[16:19], v[40:43], v[44:47]
	v_mfma_f32_16x16x32_bf16 v[36:39], v[32:35], v[40:43], v[36:39]
	v_mfma_f32_16x16x32_bf16 v[40:43], v[16:19], v[52:55], v[56:59]
	s_waitcnt lgkmcnt(0)
	v_mfma_f32_16x16x32_bf16 v[8:11], v[16:19], v[64:67], v[8:11]
	ds_read_b128 v[16:19], v68 offset:128
	v_mfma_f32_16x16x32_bf16 v[48:51], v[28:31], v[48:51], 0
	v_mfma_f32_16x16x32_bf16 v[28:31], v[28:31], v[60:63], 0
	v_mfma_f32_16x16x32_bf16 v[44:47], v[32:35], v[52:55], v[48:51]
	v_mfma_f32_16x16x32_bf16 v[28:31], v[32:35], v[64:67], v[28:31]
	ds_read_b128 v[32:35], v2 offset:34944
	s_nop 3
	ds_read_b128 v[48:51], v68 offset:192
	ds_read_b128 v[52:55], v2 offset:35008
	ds_read_b128 v[56:59], v68 offset:4480
	ds_read_b128 v[60:63], v68 offset:4544
	s_waitcnt lgkmcnt(4)
	v_mfma_f32_16x16x32_bf16 v[24:27], v[16:19], v[32:35], v[24:27]
	s_waitcnt lgkmcnt(1)
	v_mfma_f32_16x16x32_bf16 v[12:15], v[56:59], v[32:35], v[12:15]
	ds_read_b128 v[32:35], v2 offset:39296
	ds_read_b128 v[64:67], v2 offset:39360
	s_waitcnt lgkmcnt(1)
	v_mfma_f32_16x16x32_bf16 v[20:23], v[16:19], v[32:35], v[20:23]
	v_mfma_f32_16x16x32_bf16 v[32:35], v[56:59], v[32:35], v[36:39]
	s_nop 2
	ds_read_b128 v[36:39], v2 offset:43648
	ds_read_b128 v[68:71], v2 offset:43712
	s_waitcnt lgkmcnt(1)
	v_mfma_f32_16x16x32_bf16 v[40:43], v[16:19], v[36:39], v[40:43]
	v_mfma_f32_16x16x32_bf16 v[36:39], v[56:59], v[36:39], v[44:47]
	s_nop 2
	ds_read_b128 v[44:47], v2 offset:48000
	ds_read_b128 v[72:75], v2 offset:48064
	v_lshlrev_b32_e32 v2, 7, v77
	v_ashrrev_i32_e32 v3, 31, v2
	v_lshlrev_b64 v[2:3], 2, v[2:3]
	v_or3_b32 v2, v0, v76, v2
	v_lshl_add_u64 v[2:3], s[18:19], 0, v[2:3]
	s_waitcnt lgkmcnt(1)
	v_mfma_f32_16x16x32_bf16 v[8:11], v[16:19], v[44:47], v[8:11]
	s_add_u32 s18, s18, s14
	s_addc_u32 s19, s19, s15
	s_cmpk_gt_i32 s39, 0x7ff
	v_mfma_f32_16x16x32_bf16 v[16:19], v[56:59], v[44:47], v[28:31]
	v_add_co_u32_e32 v44, vcc, s31, v2
	v_mfma_f32_16x16x32_bf16 v[24:27], v[48:51], v[52:55], v[24:27]
	s_nop 0
	v_addc_co_u32_e32 v45, vcc, -1, v3, vcc
	v_add_co_u32_e32 v46, vcc, s34, v2
	v_mfma_f32_16x16x32_bf16 v[12:15], v[60:63], v[52:55], v[12:15]
	s_nop 0
	v_addc_co_u32_e32 v47, vcc, -1, v3, vcc
	v_mfma_f32_16x16x32_bf16 v[20:23], v[48:51], v[64:67], v[20:23]
	v_mfma_f32_16x16x32_bf16 v[28:31], v[60:63], v[64:67], v[32:35]
	v_mfma_f32_16x16x32_bf16 v[32:35], v[48:51], v[68:71], v[40:43]
	s_nop 2
	v_add_co_u32_e32 v40, vcc, s24, v2
	v_mfma_f32_16x16x32_bf16 v[36:39], v[60:63], v[68:71], v[36:39]
	s_nop 0
	v_addc_co_u32_e32 v41, vcc, -1, v3, vcc
	s_waitcnt lgkmcnt(0)
	v_mfma_f32_16x16x32_bf16 v[8:11], v[48:51], v[72:75], v[8:11]
	v_mfma_f32_16x16x32_bf16 v[16:19], v[60:63], v[72:75], v[16:19]
	global_store_dwordx4 v[44:45], v[24:27], off offset:-64
	global_store_dwordx4 v[44:45], v[12:15], off
	global_store_dwordx4 v[46:47], v[20:23], off offset:-64
	global_store_dwordx4 v[46:47], v[28:31], off
	global_store_dwordx4 v[40:41], v[32:35], off offset:-64
	global_store_dwordx4 v[40:41], v[36:39], off
	s_nop 0
	global_store_dwordx4 v[2:3], v[8:11], off offset:-64
	global_store_dwordx4 v[2:3], v[16:19], off
	s_barrier
	s_cbranch_scc0 .LBB0_220
	s_branch .LBB0_217
